# mLSTM chunk loop: packed K scaling (v_pk_mul + paired bf16 cvt), next-chunk load addresses via SALU base + per-lane offsets
# baseline (speedup 1.0000x reference)
; #define LAS __attribute__((address_space(3)))
; template <bool INSYNC> DI void mlstm_phase(const Ctx& C, const bf16* PROJ, const f32x4* TAB, const bf16* PP, bf16* HF, bf16* HB, const XcdBarrier& xbar) {
;     ...
;         f32x4 Sacc[2][2], nacc[2];
; #pragma unroll
;         for (int i = 0; i < 2; ++i) { nacc[i] = (f32x4){0.f, 0.f, 0.f, 0.f};
; #pragma unroll
;             for (int j = 0; j < 2; ++j) Sacc[i][j] = (f32x4){0.f, 0.f, 0.f, 0.f}; }
;         float m_st = 0.f;
;         for (int i = tid; i < 32 * LQ / 2; i += NTHR) ((LAS unsigned*)ST)[i] = 0u;
;         if (tid < 128) ((LAS unsigned*)NB)[tid] = 0u;
;         v4u qreg[4], ktr[4], preg; v2u vreg; f32x4 tg = (f32x4){0.f, 0.f, 0.f, 0.f};
;     ...
;         MLSTM_LOAD(0);
;         __syncthreads();
.LBB0_1401:
	s_and_b32 s13, s34, 64
	s_ashr_i32 s12, s14, 3
	s_cmp_eq_u32 s13, 0
	s_cselect_b64 s[50:51], -1, 0
	s_and_b64 s[16:17], s[50:51], exec
	s_mov_b32 s5, 0x29000000
	s_cselect_b32 s13, 0x27000000, s5
	s_add_u32 s52, s72, s13
	v_cndmask_b32_e64 v0, v134, v133, s[50:51]
	s_addc_u32 s53, s73, 0
	s_ashr_i32 s13, s12, 31
	s_lshl_b64 s[12:13], s[12:13], 13
	v_ashrrev_i32_e32 v1, 31, v0
	s_lshl_b32 s16, s14, 7
	v_lshl_add_u64 v[0:1], s[12:13], 0, v[0:1]
	v_mov_b64_e32 v[6:7], s[86:87]
	s_and_b32 s20, s16, 0x300
	v_mad_u64_u32 v[12:13], s[16:17], v0, s63, v[6:7]
	v_mad_i32_i24 v13, v1, s63, v13
	s_lshl_b32 s92, s20, 1
	v_lshl_add_u64 v[0:1], v[12:13], 0, s[92:93]
	v_cndmask_b32_e64 v12, v136, v135, s[50:51]
	v_ashrrev_i32_e32 v13, 31, v12
	v_lshl_add_u64 v[12:13], s[12:13], 0, v[12:13]
	v_mad_u64_u32 v[14:15], s[16:17], v12, s63, v[6:7]
	v_lshl_add_u64 v[0:1], v[0:1], 0, v[2:3]
	v_mad_i32_i24 v15, v13, s63, v15
	v_add_co_u32_e32 v0, vcc, s29, v0
	v_lshl_add_u64 v[12:13], v[14:15], 0, s[92:93]
	s_nop 0
	v_addc_co_u32_e32 v1, vcc, 0, v1, vcc
	v_lshl_add_u64 v[12:13], v[12:13], 0, v[2:3]
	v_add_co_u32_e32 v16, vcc, s29, v12
	s_mov_b32 s22, 0
	s_nop 0
	v_addc_co_u32_e32 v17, vcc, 0, v13, vcc
	global_load_dwordx4 v[12:15], v[0:1], off
	s_nop 0
	global_load_dwordx4 v[16:19], v[16:17], off
	v_cndmask_b32_e64 v0, v138, v137, s[50:51]
	v_ashrrev_i32_e32 v1, 31, v0
	v_lshl_add_u64 v[0:1], s[12:13], 0, v[0:1]
	v_mad_u64_u32 v[20:21], s[16:17], v0, s63, v[6:7]
	v_mad_i32_i24 v21, v1, s63, v21
	v_lshl_add_u64 v[0:1], v[20:21], 0, s[92:93]
	v_cndmask_b32_e64 v20, v140, v139, s[50:51]
	v_ashrrev_i32_e32 v21, 31, v20
	v_lshl_add_u64 v[20:21], s[12:13], 0, v[20:21]
	v_mad_u64_u32 v[22:23], s[16:17], v20, s63, v[6:7]
	v_lshl_add_u64 v[0:1], v[0:1], 0, v[2:3]
	v_mad_i32_i24 v23, v21, s63, v23
	v_add_co_u32_e32 v0, vcc, s29, v0
	v_lshl_add_u64 v[20:21], v[22:23], 0, s[92:93]
	s_nop 0
	v_addc_co_u32_e32 v1, vcc, 0, v1, vcc
	v_lshl_add_u64 v[20:21], v[20:21], 0, v[2:3]
	v_add_co_u32_e32 v20, vcc, s29, v20
	v_mov_b32_e32 v117, 0
	s_nop 0
	v_addc_co_u32_e32 v21, vcc, 0, v21, vcc
	global_load_dwordx4 v[24:27], v[0:1], off
	global_load_dwordx4 v[32:35], v[20:21], off
	v_cndmask_b32_e64 v0, v122, v120, s[50:51]
	v_or_b32_e32 v0, s12, v0
	v_mad_u64_u32 v[0:1], s[16:17], v0, s63, v[6:7]
	v_mad_i32_i24 v1, s13, v226, v1
	v_lshl_add_u64 v[0:1], v[0:1], 0, s[92:93]
	v_lshl_add_u64 v[6:7], s[80:81], 1, v[0:1]
	s_mov_b64 s[16:17], 0x1800
	v_lshl_add_u64 v[20:21], v[6:7], 0, s[16:17]
	s_lshl_b32 s16, s34, 2
	s_and_b32 s21, s16, 0xe0
	s_lshl_b32 s16, s21, 1
	s_mov_b32 s17, s93
	v_add_co_u32_e32 v6, vcc, s29, v6
	v_lshl_add_u64 v[0:1], v[0:1], 0, s[16:17]
	s_nop 0
	v_addc_co_u32_e32 v7, vcc, 0, v7, vcc
	v_lshl_add_u64 v[0:1], s[8:9], 1, v[0:1]
	global_load_dwordx4 v[48:51], v[20:21], off offset:16
	global_load_dwordx4 v[56:59], v[20:21], off offset:32
	global_load_dwordx4 v[60:63], v[6:7], off offset:2048
	global_load_dwordx4 v[64:67], v[20:21], off offset:48
	v_add_co_u32_e32 v0, vcc, s28, v0
	s_lshl_b64 s[16:17], s[14:15], 20
	s_nop 0
	v_addc_co_u32_e32 v1, vcc, 0, v1, vcc
	v_lshl_add_u64 v[6:7], v[114:115], 0, s[16:17]
	global_load_dwordx2 v[118:119], v[0:1], off
	global_load_dwordx4 v[68:71], v[6:7], off
	v_or_b32_e32 v0, s21, v129
	s_lshl_b64 s[14:15], s[14:15], 7
	v_or_b32_e32 v0, s20, v0
	s_add_u32 s16, s86, s92
	v_lshlrev_b32_e32 v0, 1, v0
	v_mov_b32_e32 v1, v3
	s_addc_u32 s17, s87, 0
	v_lshl_add_u64 v[0:1], s[52:53], 0, v[0:1]
	v_mov_b32_e32 v20, 0
	v_mov_b32_e32 v21, 0
	v_mov_b32_e32 v22, 0
	v_mov_b32_e32 v23, 0
	v_mov_b32_e32 v28, 0
	v_mov_b32_e32 v29, 0
	v_mov_b32_e32 v30, 0
	v_mov_b32_e32 v31, 0
	v_mov_b32_e32 v36, 0
	v_mov_b32_e32 v37, 0
	v_mov_b32_e32 v38, 0
	v_mov_b32_e32 v39, 0
	v_mov_b32_e32 v40, 0
	v_mov_b32_e32 v41, 0
	v_mov_b32_e32 v42, 0
	v_mov_b32_e32 v43, 0
	v_mov_b32_e32 v44, 0
	v_mov_b32_e32 v45, 0
	v_mov_b32_e32 v46, 0
	v_mov_b32_e32 v47, 0
	v_mov_b32_e32 v52, 0
	v_mov_b32_e32 v53, 0
	v_mov_b32_e32 v54, 0
	v_mov_b32_e32 v55, 0
	s_lshl_b32 s92, s20, 1
	s_lshl_b32 s66, s21, 1
	v_cndmask_b32_e64 v6, v134, v133, s[50:51]
	v_mul_lo_u32 v6, v6, s63
	v_add_u32_e32 v158, v6, v2
	v_cndmask_b32_e64 v6, v136, v135, s[50:51]
	v_mul_lo_u32 v6, v6, s63
	v_add_u32_e32 v159, v6, v2
	v_cndmask_b32_e64 v6, v138, v137, s[50:51]
	v_mul_lo_u32 v6, v6, s63
	v_add_u32_e32 v160, v6, v2
	v_cndmask_b32_e64 v6, v140, v139, s[50:51]
	v_mul_lo_u32 v6, v6, s63
	v_add_u32_e32 v171, v6, v2
	v_cndmask_b32_e64 v6, v122, v120, s[50:51]
	v_mul_lo_u32 v250, v6, s63
	s_waitcnt vmcnt(0) lgkmcnt(0)
	s_barrier
	s_branch .LBB0_1403

; #define LAS __attribute__((address_space(3)))
; DI float bflo(unsigned w) { return __uint_as_float(w << 16); }
; DI float bfhi(unsigned w) { return __uint_as_float(w & 0xffff0000u); }
; DI bf16 f2bf(float f) { return (bf16)(pk2(f, 0.f) & 0xffffu); }
; template <bool INSYNC> DI void mlstm_phase(const Ctx& C, const bf16* PROJ, const f32x4* TAB, const bf16* PP, bf16* HF, bf16* HB, const XcdBarrier& xbar) {
;     ...
;             for (int i = 0; i < 4; ++i) { const int idx = tid + NTHR * i, row = idx >> 5, cc = idx & 31; *(LAS v4u*)(Qs + row * LQ + 8 * cc) = qreg[i]; }
;             { const float ws = s_ws[lane];
; #pragma unroll
;                 for (int i = 0; i < 4; ++i) { const v4u k = ktr[i]; LAS bf16* kt = KT + (32 * w + 8 * i) * LT + lane;
;                     kt[0 * LT] = f2bf(bflo(k.x) * ws); kt[1 * LT] = f2bf(bfhi(k.x) * ws); kt[2 * LT] = f2bf(bflo(k.y) * ws); kt[3 * LT] = f2bf(bfhi(k.y) * ws);
;                     kt[4 * LT] = f2bf(bflo(k.z) * ws); kt[5 * LT] = f2bf(bfhi(k.z) * ws); kt[6 * LT] = f2bf(bflo(k.w) * ws); kt[7 * LT] = f2bf(bfhi(k.w) * ws); }
;                 LAS bf16* vt = VT + (4 * w) * LT + lane; const v2u v = vreg;
;                 vt[0 * LT] = (bf16)(v.x & 0xffffu); vt[1 * LT] = (bf16)(v.x >> 16); vt[2 * LT] = (bf16)(v.y & 0xffffu); vt[3 * LT] = (bf16)(v.y >> 16); }
;             *(LAS v4u*)(Ps + (tid >> 3) * LT + 8 * (tid & 7)) = preg;
.LBB0_1461:
	v_readlane_b32 s5, v253, 3
	s_waitcnt lgkmcnt(0)
	s_barrier
	s_waitcnt vmcnt(4)
	s_waitcnt lgkmcnt(4)
	v_mov_b32_e32 v5, s5
	ds_read_b64 v[116:117], v5
	ds_write_b128 v149, v[12:15]
	ds_write_b128 v152, v[16:19]
	ds_write_b128 v162, v[24:27]
	ds_write_b128 v163, v[32:35]
	ds_read_b32 v5, v124
	s_add_i32 s22, s35, 1
	s_cmpk_eq_i32 s35, 0x7f
	s_waitcnt lgkmcnt(0)
	v_lshlrev_b32_e32 v6, 16, v60
	v_and_b32_e32 v7, 0xffff0000, v60
	v_lshlrev_b32_e32 v72, 16, v61
	v_and_b32_e32 v73, 0xffff0000, v61
	v_pk_mul_f32 v[6:7], v[6:7], v[4:5] op_sel:[0,1]
	v_pk_mul_f32 v[72:73], v[72:73], v[4:5] op_sel:[0,1]
	v_cvt_pk_bf16_f32 v6, v6, v7
	v_cvt_pk_bf16_f32 v72, v72, v73
	ds_write_b16 v164, v6 offset:33792
	ds_write_b16_d16_hi v164, v6 offset:33936
	ds_write_b16 v164, v72 offset:34080
	ds_write_b16_d16_hi v164, v72 offset:34224
	v_lshlrev_b32_e32 v6, 16, v62
	v_and_b32_e32 v7, 0xffff0000, v62
	v_lshlrev_b32_e32 v72, 16, v63
	v_and_b32_e32 v73, 0xffff0000, v63
	v_pk_mul_f32 v[6:7], v[6:7], v[4:5] op_sel:[0,1]
	v_pk_mul_f32 v[72:73], v[72:73], v[4:5] op_sel:[0,1]
	v_cvt_pk_bf16_f32 v6, v6, v7
	v_cvt_pk_bf16_f32 v72, v72, v73
	ds_write_b16 v164, v6 offset:34368
	ds_write_b16_d16_hi v164, v6 offset:34512
	ds_write_b16 v164, v72 offset:34656
	ds_write_b16_d16_hi v164, v72 offset:34800
	v_lshlrev_b32_e32 v6, 16, v48
	v_and_b32_e32 v7, 0xffff0000, v48
	v_lshlrev_b32_e32 v72, 16, v49
	v_and_b32_e32 v73, 0xffff0000, v49
	v_pk_mul_f32 v[6:7], v[6:7], v[4:5] op_sel:[0,1]
	v_pk_mul_f32 v[72:73], v[72:73], v[4:5] op_sel:[0,1]
	v_cvt_pk_bf16_f32 v6, v6, v7
	v_cvt_pk_bf16_f32 v72, v72, v73
	ds_write_b16 v164, v6 offset:34944
	ds_write_b16_d16_hi v164, v6 offset:35088
	ds_write_b16 v164, v72 offset:35232
	ds_write_b16_d16_hi v164, v72 offset:35376
	v_lshlrev_b32_e32 v6, 16, v50
	v_and_b32_e32 v7, 0xffff0000, v50
	v_lshlrev_b32_e32 v72, 16, v51
	v_and_b32_e32 v73, 0xffff0000, v51
	v_pk_mul_f32 v[6:7], v[6:7], v[4:5] op_sel:[0,1]
	v_pk_mul_f32 v[72:73], v[72:73], v[4:5] op_sel:[0,1]
	v_cvt_pk_bf16_f32 v6, v6, v7
	v_cvt_pk_bf16_f32 v72, v72, v73
	ds_write_b16 v164, v6 offset:35520
	ds_write_b16_d16_hi v164, v6 offset:35664
	ds_write_b16 v164, v72 offset:35808
	ds_write_b16_d16_hi v164, v72 offset:35952
	v_lshlrev_b32_e32 v6, 16, v56
	v_and_b32_e32 v7, 0xffff0000, v56
	v_lshlrev_b32_e32 v72, 16, v57
	v_and_b32_e32 v73, 0xffff0000, v57
	v_pk_mul_f32 v[6:7], v[6:7], v[4:5] op_sel:[0,1]
	v_pk_mul_f32 v[72:73], v[72:73], v[4:5] op_sel:[0,1]
	v_cvt_pk_bf16_f32 v6, v6, v7
	v_cvt_pk_bf16_f32 v72, v72, v73
	ds_write_b16 v164, v6 offset:36096
	ds_write_b16_d16_hi v164, v6 offset:36240
	ds_write_b16 v164, v72 offset:36384
	ds_write_b16_d16_hi v164, v72 offset:36528
	v_lshlrev_b32_e32 v6, 16, v58
	v_and_b32_e32 v7, 0xffff0000, v58
	v_lshlrev_b32_e32 v72, 16, v59
	v_and_b32_e32 v73, 0xffff0000, v59
	v_pk_mul_f32 v[6:7], v[6:7], v[4:5] op_sel:[0,1]
	v_pk_mul_f32 v[72:73], v[72:73], v[4:5] op_sel:[0,1]
	v_cvt_pk_bf16_f32 v6, v6, v7
	v_cvt_pk_bf16_f32 v72, v72, v73
	ds_write_b16 v164, v6 offset:36672
	ds_write_b16_d16_hi v164, v6 offset:36816
	ds_write_b16 v164, v72 offset:36960
	ds_write_b16_d16_hi v164, v72 offset:37104
	v_lshlrev_b32_e32 v6, 16, v64
	v_and_b32_e32 v7, 0xffff0000, v64
	v_lshlrev_b32_e32 v72, 16, v65
	v_and_b32_e32 v73, 0xffff0000, v65
	v_pk_mul_f32 v[6:7], v[6:7], v[4:5] op_sel:[0,1]
	v_pk_mul_f32 v[72:73], v[72:73], v[4:5] op_sel:[0,1]
	v_cvt_pk_bf16_f32 v6, v6, v7
	v_cvt_pk_bf16_f32 v72, v72, v73
	ds_write_b16 v164, v6 offset:37248
	ds_write_b16_d16_hi v164, v6 offset:37392
	ds_write_b16 v164, v72 offset:37536
	ds_write_b16_d16_hi v164, v72 offset:37680
	v_lshlrev_b32_e32 v6, 16, v66
	v_and_b32_e32 v7, 0xffff0000, v66
	v_lshlrev_b32_e32 v72, 16, v67
	v_and_b32_e32 v73, 0xffff0000, v67
	v_pk_mul_f32 v[6:7], v[6:7], v[4:5] op_sel:[0,1]
	v_pk_mul_f32 v[72:73], v[72:73], v[4:5] op_sel:[0,1]
	v_cvt_pk_bf16_f32 v6, v6, v7
	v_cvt_pk_bf16_f32 v72, v72, v73
	ds_write_b16 v164, v6 offset:37824
	ds_write_b16_d16_hi v164, v6 offset:37968
	ds_write_b16 v164, v72 offset:38112
	ds_write_b16_d16_hi v164, v72 offset:38256
	ds_write_b16 v165, v118
	ds_write_b16_d16_hi v165, v118 offset:144
	ds_write_b16 v165, v119 offset:288
	ds_write_b16_d16_hi v165, v119 offset:432
	ds_write_b128 v166, v[68:71]
	s_cbranch_scc1 .LBB0_1467
	s_andn2_b64 vcc, exec, s[82:83]
	s_mov_b64 s[20:21], -1
	s_cbranch_vccnz .LBB0_1464
	s_add_u32 s52, s14, s22
	s_addc_u32 s53, s15, 0
	s_mov_b64 s[20:21], 0

; template <bool INSYNC> DI void mlstm_phase(const Ctx& C, const bf16* PROJ, const f32x4* TAB, const bf16* PP, bf16* HF, bf16* HB, const XcdBarrier& xbar) {
;     ...
;             if (c + 1 < SEQ / 64) MLSTM_LOAD(c + 1);
.LBB0_1466:
	s_lshl_b32 s23, s22, 6
	s_mul_i32 s23, s23, s63
	s_sub_i32 s18, 0, s23
	s_cmp_lg_u32 s50, 0
	s_cselect_b32 s23, s23, s18
	s_ashr_i32 s19, s23, 31
	s_mul_i32 s18, s12, s63
	s_add_u32 s18, s18, s23
	s_addc_u32 s19, s19, 0
	s_add_u32 s20, s86, s92
	s_addc_u32 s21, s87, s93
	s_add_u32 s20, s20, s29
	s_addc_u32 s21, s21, 0
	s_add_u32 s20, s20, s18
	s_addc_u32 s21, s21, s19
	global_load_dwordx4 v[12:15], v158, s[20:21]
	global_load_dwordx4 v[16:19], v159, s[20:21]
	global_load_dwordx4 v[24:27], v160, s[20:21]
	global_load_dwordx4 v[32:35], v171, s[20:21]
	s_add_u32 s20, s16, s18
	s_addc_u32 s21, s17, s19
	s_mov_b32 s67, s93
	s_lshl_b64 s[18:19], s[8:9], 1
	s_add_u32 s18, s18, s20
	s_addc_u32 s19, s19, s21
	s_add_u32 s18, s18, s66
	s_addc_u32 s19, s19, s67
	s_add_u32 s18, s18, s28
	s_addc_u32 s19, s19, 0
	s_lshl_b64 s[52:53], s[80:81], 1
	s_add_u32 s20, s20, s52
	s_addc_u32 s21, s21, s53
	global_load_dwordx2 v[118:119], v250, s[18:19]
	s_add_u32 s18, s20, s29
	s_addc_u32 s19, s21, 0
	s_add_u32 s20, s20, 0x1800
	s_addc_u32 s21, s21, 0
	global_load_dwordx4 v[60:63], v250, s[18:19] offset:2048
	global_load_dwordx4 v[48:51], v250, s[20:21] offset:16
	global_load_dwordx4 v[56:59], v250, s[20:21] offset:32
	global_load_dwordx4 v[64:67], v250, s[20:21] offset:48
	s_add_u32 s52, s14, s22
	s_addc_u32 s53, s15, 0
	s_lshl_b64 s[20:21], s[52:53], 13
	v_lshl_add_u64 v[68:69], v[114:115], 0, s[20:21]
	global_load_dwordx4 v[68:71], v[68:69], off
